# attention: PV-read barrier moved ahead of last PV MFMA group; K/V LDS-DMA issue interleaved under PV MFMAs
# baseline (speedup 1.0000x reference)
; #define SBAR() __builtin_amdgcn_sched_barrier(0)
; #define SLOAD(i, k0) do { const unsigned so_ = (unsigned)(k0) * (LDK * 2); \
;     sr_[i].vs0 = BLD8(srV, kvoff, so_); sr_[i].vs1 = BLD8(srV, kvoff + 32u * LDK * 2u, so_); \
;     sr_[i].ks0 = BLD8(srK, kvoff, so_); sr_[i].ks1 = BLD8(srK, kvoff + 32u * LDK * 2u, so_); } while (0)
; template <int D0> __device__ __forceinline__ void pv_one(f32x16& od, int vb, bf16x8 pa0, bf16x8 pa1, bf16x8 pa2, bf16x8 pa3) {
;   const s16x4 l0 = tr_read<v_rd_off(D0, 0, 0)>(vb), h0 = tr_read<v_rd_off(D0, 0, 1)>(vb), l1 = tr_read<v_rd_off(D0, 1, 0)>(vb), h1 = tr_read<v_rd_off(D0, 1, 1)>(vb);
;   const s16x4 l2 = tr_read<v_rd_off(D0, 2, 0)>(vb), h2 = tr_read<v_rd_off(D0, 2, 1)>(vb), l3 = tr_read<v_rd_off(D0, 3, 0)>(vb), h3 = tr_read<v_rd_off(D0, 3, 1)>(vb);
;   asm volatile("s_waitcnt lgkmcnt(0)" ::: "memory"); SBAR();
;     ...
;   od = __builtin_amdgcn_mfma_f32_32x32x16_bf16(pa0, PK(l0, h0), od, 0, 0, 0);
;   od = __builtin_amdgcn_mfma_f32_32x32x16_bf16(pa1, PK(l1, h1), od, 0, 0, 0);
;   od = __builtin_amdgcn_mfma_f32_32x32x16_bf16(pa2, PK(l2, h2), od, 0, 0, 0);
;   od = __builtin_amdgcn_mfma_f32_32x32x16_bf16(pa3, PK(l3, h3), od, 0, 0, 0);
;     ...
; }
; __device__ __forceinline__ void pv_d0(f32x16* o, int vb, bf16x8 pa0, bf16x8 pa1, bf16x8 pa2, bf16x8 pa3) {
;   pv_one<0>(o[0], vb, pa0, pa1, pa2, pa3); pv_one<1>(o[1], vb, pa0, pa1, pa2, pa3); pv_one<2>(o[2], vb, pa0, pa1, pa2, pa3); pv_one<3>(o[3], vb, pa0, pa1, pa2, pa3);
; __device__ __forceinline__ void attn_dense_body(const bf16* Qb, const bf16* __restrict__ Kh, const bf16* __restrict__ Vh,
;                                                 bf16* Ob, int seq, char* lds, const float* __restrict__ qg, const float* __restrict__ rope, int s0) {
;     ...
;     SBAR(); qkt(pB0, pB1, (bf16*)((char*)K_lds + SHM_K), qr, negm, r32, hi);
;     finishSM(pA0, pA1, alA, l_reg, pa0, pa1, pa2, pa3); SBAR();
;     SLOAD(SO, (j + 1) * KVBLK); SBAR();
;     pv_d0(o, vb0, pa0, pa1, pa2, pa3); partialSM<false>(pB0, pB1, m_reg, negm, alB);
.LBB0_96:
	ds_read_b128 v[230:233], v216 offset:57344
	ds_read_b128 v[112:115], v216 offset:49152
	v_add_f32_e32 v178, 0, v245
	v_add_f32_e32 v178, v247, v178
	v_add_f32_e32 v178, v179, v178
	v_add_f32_e32 v178, v246, v178
	s_waitcnt lgkmcnt(0)
	v_mfma_f32_32x32x16_bf16 v[128:143], v[112:115], v[146:149], v[80:95]
	v_add_f32_e32 v178, v180, v178
	v_add_f32_e32 v178, v244, v178
	v_mfma_f32_32x32x16_bf16 v[112:127], v[230:233], v[146:149], v[80:95]
	ds_read_b128 v[230:233], v224 offset:57344
	ds_read_b128 v[248:251], v224 offset:49152
	v_add_f32_e32 v178, v181, v178
	v_add_f32_e32 v178, v243, v178
	v_add_f32_e32 v178, v240, v178
	v_add_f32_e32 v178, v242, v178
	v_add_f32_e32 v178, v239, v178
	v_add_f32_e32 v178, v241, v178
	s_waitcnt lgkmcnt(0)
	v_mfma_f32_32x32x16_bf16 v[128:143], v[248:251], v[150:153], v[128:143]
	v_exp_f32_e32 v96, v96
	v_add_f32_e32 v178, v236, v178
	v_exp_f32_e32 v97, v97
	v_add_f32_e32 v178, v238, v178
	v_exp_f32_e32 v98, v98
	v_add_f32_e32 v178, v235, v178
	v_exp_f32_e32 v99, v99
	v_mfma_f32_32x32x16_bf16 v[112:127], v[230:233], v[150:153], v[112:127]
	ds_read_b128 v[230:233], v223 offset:57344
	ds_read_b128 v[248:251], v223 offset:49152
	v_add_f32_e32 v178, v237, v178
	v_exp_f32_e32 v100, v100
	v_add_f32_e32 v178, v96, v178
	v_exp_f32_e32 v101, v101
	v_add_f32_e32 v178, v97, v178
	v_exp_f32_e32 v102, v102
	s_waitcnt lgkmcnt(0)
	v_mfma_f32_32x32x16_bf16 v[128:143], v[248:251], v[154:157], v[128:143]
	v_add_f32_e32 v178, v98, v178
	v_exp_f32_e32 v103, v103
	v_add_f32_e32 v178, v99, v178
	v_exp_f32_e32 v104, v104
	v_add_f32_e32 v178, v100, v178
	v_exp_f32_e32 v105, v105
	v_add_f32_e32 v178, v101, v178
	v_mfma_f32_32x32x16_bf16 v[112:127], v[230:233], v[154:157], v[112:127]
	ds_read_b128 v[230:233], v221 offset:57344
	ds_read_b128 v[248:251], v221 offset:49152
	v_exp_f32_e32 v106, v106
	v_add_f32_e32 v178, v102, v178
	v_exp_f32_e32 v107, v107
	v_add_f32_e32 v178, v103, v178
	v_exp_f32_e32 v108, v108
	v_add_f32_e32 v178, v104, v178
	s_waitcnt lgkmcnt(0)
	v_mfma_f32_32x32x16_bf16 v[128:143], v[248:251], v[158:161], v[128:143]
	v_exp_f32_e32 v109, v109
	v_add_f32_e32 v178, v105, v178
	v_exp_f32_e32 v110, v110
	v_add_f32_e32 v178, v106, v178
	v_exp_f32_e32 v111, v111
	v_add_f32_e32 v178, v107, v178
	v_add_f32_e32 v178, v108, v178
	v_mfma_f32_32x32x16_bf16 v[112:127], v[230:233], v[158:161], v[112:127]
	ds_read_b128 v[230:233], v222 offset:57344
	ds_read_b128 v[248:251], v222 offset:49152
	v_add_f32_e32 v178, v109, v178
	v_add_f32_e32 v178, v110, v178
	s_waitcnt lgkmcnt(0)
	v_mfma_f32_32x32x16_bf16 v[128:143], v[248:251], v[162:165], v[128:143]
	v_mfma_f32_32x32x16_bf16 v[112:127], v[230:233], v[162:165], v[112:127]
	ds_read_b128 v[230:233], v225 offset:57344
	ds_read_b128 v[248:251], v225 offset:49152
	s_waitcnt lgkmcnt(0)
	v_mfma_f32_32x32x16_bf16 v[128:143], v[248:251], v[166:169], v[128:143]
	v_mfma_f32_32x32x16_bf16 v[112:127], v[230:233], v[166:169], v[112:127]
	ds_read_b128 v[230:233], v226 offset:57344
	ds_read_b128 v[248:251], v226 offset:49152
	s_waitcnt lgkmcnt(0)
	v_mfma_f32_32x32x16_bf16 v[128:143], v[248:251], v[170:173], v[128:143]
	v_mfma_f32_32x32x16_bf16 v[112:127], v[230:233], v[170:173], v[112:127]
	ds_read_b128 v[230:233], v227 offset:57344
	ds_read_b128 v[248:251], v227 offset:49152
	s_waitcnt lgkmcnt(0)
	v_mfma_f32_32x32x16_bf16 v[128:143], v[248:251], v[174:177], v[128:143]
	v_mfma_f32_32x32x16_bf16 v[112:127], v[230:233], v[174:177], v[112:127]
	v_add_f32_e32 v230, v111, v178
	v_mov_b32_e32 v231, v230
	v_cvt_pk_bf16_f32 v178, v245, v247
	v_cvt_pk_bf16_f32 v179, v179, v246
	v_cvt_pk_bf16_f32 v180, v180, v244
	s_nop 1
	v_permlane32_swap_b32_e32 v230, v231
	v_cvt_pk_bf16_f32 v181, v181, v243
	v_permlane32_swap_b32_e32 v178, v180
	v_cvt_pk_bf16_f32 v232, v240, v242
	v_cvt_pk_bf16_f32 v233, v239, v241
	v_cvt_pk_bf16_f32 v234, v236, v238
	v_cvt_pk_bf16_f32 v235, v235, v237
	v_cvt_pk_bf16_f32 v236, v96, v97
	v_cvt_pk_bf16_f32 v237, v98, v99
	v_cvt_pk_bf16_f32 v238, v100, v101
	v_cvt_pk_bf16_f32 v239, v102, v103
	v_cvt_pk_bf16_f32 v240, v104, v105
	v_cvt_pk_bf16_f32 v241, v106, v107
	v_cvt_pk_bf16_f32 v242, v108, v109
	v_cvt_pk_bf16_f32 v243, v110, v111
	v_permlane32_swap_b32_e32 v179, v181
	v_permlane32_swap_b32_e32 v232, v234
	v_permlane32_swap_b32_e32 v233, v235
	v_permlane32_swap_b32_e32 v236, v238
	v_permlane32_swap_b32_e32 v237, v239
	v_permlane32_swap_b32_e32 v240, v242
	v_permlane32_swap_b32_e32 v241, v243
	s_add_i32 s25, s1, 0xffff8000
	s_mov_b32 s58, s90
	s_mov_b32 s59, s91
	ds_read_b64_tr_b16 v[244:245], v213 offset:0
	ds_read_b64_tr_b16 v[246:247], v213 offset:0x800
	ds_read_b64_tr_b16 v[248:249], v213 offset:0x1000
	ds_read_b64_tr_b16 v[250:251], v213 offset:0x1800
	ds_read_b64_tr_b16 v[186:187], v213 offset:0x2000
	ds_read_b64_tr_b16 v[188:189], v213 offset:0x2800
	ds_read_b64_tr_b16 v[204:205], v213 offset:0x3000
	ds_read_b64_tr_b16 v[206:207], v213 offset:0x3800
	s_waitcnt lgkmcnt(0)
	s_nop 0
	v_mfma_f32_32x32x16_bf16 v[0:15], v[178:181], v[244:247], v[0:15]
	v_mfma_f32_32x32x16_bf16 v[0:15], v[232:235], v[248:251], v[0:15]
	v_mfma_f32_32x32x16_bf16 v[0:15], v[236:239], v[186:189], v[0:15]
	ds_read_b64_tr_b16 v[186:187], v213 offset:0x200
	ds_read_b64_tr_b16 v[188:189], v213 offset:0xa00
	v_mfma_f32_32x32x16_bf16 v[0:15], v[240:243], v[204:207], v[0:15]
	ds_read_b64_tr_b16 v[204:205], v213 offset:0x1200
	ds_read_b64_tr_b16 v[206:207], v213 offset:0x1a00
	ds_read_b64_tr_b16 v[244:245], v213 offset:0x2200
	ds_read_b64_tr_b16 v[246:247], v213 offset:0x2a00
	ds_read_b64_tr_b16 v[248:249], v213 offset:0x3200
	ds_read_b64_tr_b16 v[250:251], v213 offset:0x3a00
	s_add_i32 m0, s98, 0x8000
	s_nop 0
	buffer_load_dwordx4 v64, s[56:59], s25 offen lds
	s_add_i32 m0, s98, 0x8400
	s_nop 0
	buffer_load_dwordx4 v65, s[56:59], s25 offen lds
	s_waitcnt lgkmcnt(0)
; #define SBAR() __builtin_amdgcn_sched_barrier(0)
; #define SWRITE(b, i) do { *(bf16x8*)((char*)V_lds + (b) * SHM_V + vst0) = sr_[i].vs0;          \
;     *(bf16x8*)((char*)V_lds + (b) * SHM_V + vst1) = sr_[i].vs1; int kc = sc * 2;               \
;     *(bf16x8*)((char*)K_lds + (b) * SHM_K + KSWZ(sr, kc)) = sr_[i].ks0;                       \
;     *(bf16x8*)((char*)K_lds + (b) * SHM_K + KSWZ(32 + sr, kc)) = sr_[i].ks1; } while (0)
; #define SWAIT() asm volatile("s_waitcnt vmcnt(0)" ::: "memory")
; #define RESC(a) do { if (__any((a) < 1.f)) { if (hi == 0) al_l[r32] = (a); asm volatile("s_waitcnt lgkmcnt(0)" ::: "memory"); \
;     for (int d = 0; d < 4; ++d) for (int r = 0; r < 16; ++r) o[d][r] *= al_l[crow(r, hi)]; } } while (0)
; template <int D0> __device__ __forceinline__ void pv_one(f32x16& od, int vb, bf16x8 pa0, bf16x8 pa1, bf16x8 pa2, bf16x8 pa3) {
;   const s16x4 l0 = tr_read<v_rd_off(D0, 0, 0)>(vb), h0 = tr_read<v_rd_off(D0, 0, 1)>(vb), l1 = tr_read<v_rd_off(D0, 1, 0)>(vb), h1 = tr_read<v_rd_off(D0, 1, 1)>(vb);
;   const s16x4 l2 = tr_read<v_rd_off(D0, 2, 0)>(vb), h2 = tr_read<v_rd_off(D0, 2, 1)>(vb), l3 = tr_read<v_rd_off(D0, 3, 0)>(vb), h3 = tr_read<v_rd_off(D0, 3, 1)>(vb);
;   asm volatile("s_waitcnt lgkmcnt(0)" ::: "memory"); SBAR();
;     ...
;   od = __builtin_amdgcn_mfma_f32_32x32x16_bf16(pa0, PK(l0, h0), od, 0, 0, 0);
;   od = __builtin_amdgcn_mfma_f32_32x32x16_bf16(pa1, PK(l1, h1), od, 0, 0, 0);
;   od = __builtin_amdgcn_mfma_f32_32x32x16_bf16(pa2, PK(l2, h2), od, 0, 0, 0);
;   od = __builtin_amdgcn_mfma_f32_32x32x16_bf16(pa3, PK(l3, h3), od, 0, 0, 0);
;     ...
; }
; __device__ __forceinline__ void pv_d0(f32x16* o, int vb, bf16x8 pa0, bf16x8 pa1, bf16x8 pa2, bf16x8 pa3) {
;   pv_one<0>(o[0], vb, pa0, pa1, pa2, pa3); pv_one<1>(o[1], vb, pa0, pa1, pa2, pa3); pv_one<2>(o[2], vb, pa0, pa1, pa2, pa3); pv_one<3>(o[3], vb, pa0, pa1, pa2, pa3);
; __device__ __forceinline__ void attn_dense_body(const bf16* Qb, const bf16* __restrict__ Kh, const bf16* __restrict__ Vh,
;                                                 bf16* Ob, int seq, char* lds, const float* __restrict__ qg, const float* __restrict__ rope, int s0) {
;     ...
;     pv_d0(o, vb0, pa0, pa1, pa2, pa3); partialSM<false>(pB0, pB1, m_reg, negm, alB);
;     __syncthreads(); SWAIT(); SWRITE(0, SE);
;     RESC(alB); __syncthreads();
	v_mfma_f32_32x32x16_bf16 v[32:47], v[178:181], v[186:189], v[32:47]
	ds_read_b64_tr_b16 v[186:187], v213 offset:0x400
	ds_read_b64_tr_b16 v[188:189], v213 offset:0xc00
	v_mfma_f32_32x32x16_bf16 v[32:47], v[232:235], v[204:207], v[32:47]
	ds_read_b64_tr_b16 v[204:205], v213 offset:0x1400
	ds_read_b64_tr_b16 v[206:207], v213 offset:0x1c00
	v_mfma_f32_32x32x16_bf16 v[32:47], v[236:239], v[244:247], v[32:47]
	ds_read_b64_tr_b16 v[244:245], v213 offset:0x2400
	ds_read_b64_tr_b16 v[246:247], v213 offset:0x2c00
	v_mfma_f32_32x32x16_bf16 v[32:47], v[240:243], v[248:251], v[32:47]
	ds_read_b64_tr_b16 v[248:249], v213 offset:0x3400
	ds_read_b64_tr_b16 v[250:251], v213 offset:0x3c00
	s_waitcnt lgkmcnt(0)
	v_mfma_f32_32x32x16_bf16 v[16:31], v[178:181], v[186:189], v[16:31]
	ds_read_b64_tr_b16 v[186:187], v213 offset:0x600
	ds_read_b64_tr_b16 v[188:189], v213 offset:0xe00
	v_mfma_f32_32x32x16_bf16 v[16:31], v[232:235], v[204:207], v[16:31]
	ds_read_b64_tr_b16 v[204:205], v213 offset:0x1600
	ds_read_b64_tr_b16 v[206:207], v213 offset:0x1e00
	v_mfma_f32_32x32x16_bf16 v[16:31], v[236:239], v[244:247], v[16:31]
	ds_read_b64_tr_b16 v[244:245], v213 offset:0x2600
	ds_read_b64_tr_b16 v[246:247], v213 offset:0x2e00
	v_mfma_f32_32x32x16_bf16 v[16:31], v[240:243], v[248:251], v[16:31]
	ds_read_b64_tr_b16 v[248:249], v213 offset:0x3600
	ds_read_b64_tr_b16 v[250:251], v213 offset:0x3e00
	s_waitcnt lgkmcnt(0)
	s_barrier
	v_mfma_f32_32x32x16_bf16 v[48:63], v[178:181], v[186:189], v[48:63]
	s_mov_b32 m0, s98
	s_nop 0
	buffer_load_dwordx4 v66, s[88:91], s25 offen lds
	v_max_f32_e32 v178, v129, v129
	v_max_f32_e32 v179, v128, v128
	v_max_f32_e32 v178, v179, v178
	v_max3_f32 v178, v178, v130, v131
	v_max3_f32 v178, v178, v132, v133
	v_max3_f32 v178, v178, v134, v135
	v_max3_f32 v178, v178, v136, v137
	v_mfma_f32_32x32x16_bf16 v[48:63], v[232:235], v[204:207], v[48:63]
	s_add_i32 m0, s98, 0x400
	s_nop 0
	buffer_load_dwordx4 v67, s[88:91], s25 offen lds
	v_max3_f32 v178, v178, v138, v139
	v_max3_f32 v178, v178, v140, v141
	v_max3_f32 v178, v178, v142, v143
	v_max3_f32 v178, v178, v112, v113
	v_max3_f32 v178, v178, v114, v115
	v_max3_f32 v178, v178, v116, v117
	v_max3_f32 v178, v178, v118, v119
	v_mfma_f32_32x32x16_bf16 v[48:63], v[236:239], v[244:247], v[48:63]
	v_max3_f32 v178, v178, v120, v121
	v_max3_f32 v178, v178, v122, v123
	v_max3_f32 v178, v178, v124, v125
	v_max3_f32 v178, v178, v126, v127
	v_mov_b32_e32 v179, v178
	s_nop 1
	v_permlane32_swap_b32_e32 v178, v179
	v_mfma_f32_32x32x16_bf16 v[48:63], v[240:243], v[248:251], v[48:63]
	v_max_f32_e32 v179, v179, v179
	v_max_f32_e32 v178, v178, v178
	v_max_f32_e32 v178, v178, v179
	v_cmp_ge_f32_e32 vcc, s5, v178
	s_cmp_eq_u64 vcc, exec
	s_cbranch_scc0 .LBB0_109
	v_mov_b32_e32 v232, 1.0
.LBB0_98:
	v_cmp_gt_f32_e32 vcc, 1.0, v232
	s_cbranch_vccz .LBB0_102
	s_and_saveexec_b64 s[58:59], s[52:53]
	ds_write_b32 v211, v232 offset:128
	s_or_b64 exec, exec, s[58:59]
	s_waitcnt lgkmcnt(0)
	v_add_u32_e32 v108, v210, v194
	ds_read_b128 v[96:99], v108 offset:224
	ds_read_b128 v[100:103], v108 offset:192
	ds_read_b128 v[104:107], v108 offset:160
	ds_read_b128 v[108:111], v108 offset:128
	s_waitcnt lgkmcnt(3)
	v_pk_mul_f32 v[12:13], v[12:13], v[96:97]
	s_waitcnt lgkmcnt(2)
	v_pk_mul_f32 v[8:9], v[8:9], v[100:101]
	s_waitcnt lgkmcnt(1)
	v_pk_mul_f32 v[4:5], v[4:5], v[104:105]
	v_pk_mul_f32 v[14:15], v[14:15], v[98:99]
	v_pk_mul_f32 v[10:11], v[10:11], v[102:103]
	v_pk_mul_f32 v[6:7], v[6:7], v[106:107]
	s_waitcnt lgkmcnt(0)
	v_pk_mul_f32 v[2:3], v[2:3], v[110:111]
	v_pk_mul_f32 v[0:1], v[0:1], v[108:109]
	v_pk_mul_f32 v[44:45], v[44:45], v[96:97]
	v_pk_mul_f32 v[40:41], v[40:41], v[100:101]
	v_pk_mul_f32 v[36:37], v[36:37], v[104:105]
	v_pk_mul_f32 v[46:47], v[46:47], v[98:99]
	v_pk_mul_f32 v[42:43], v[42:43], v[102:103]
	v_pk_mul_f32 v[38:39], v[38:39], v[106:107]
	v_pk_mul_f32 v[34:35], v[34:35], v[110:111]
	v_pk_mul_f32 v[32:33], v[32:33], v[108:109]
	v_pk_mul_f32 v[28:29], v[28:29], v[96:97]
	v_pk_mul_f32 v[24:25], v[24:25], v[100:101]
	v_pk_mul_f32 v[20:21], v[20:21], v[104:105]
	v_pk_mul_f32 v[30:31], v[30:31], v[98:99]
	v_pk_mul_f32 v[26:27], v[26:27], v[102:103]
	v_pk_mul_f32 v[22:23], v[22:23], v[106:107]
	v_pk_mul_f32 v[18:19], v[18:19], v[110:111]
	v_pk_mul_f32 v[16:17], v[16:17], v[108:109]
	v_pk_mul_f32 v[60:61], v[60:61], v[96:97]
	v_pk_mul_f32 v[56:57], v[56:57], v[100:101]
	v_pk_mul_f32 v[52:53], v[52:53], v[104:105]
	v_pk_mul_f32 v[62:63], v[62:63], v[98:99]
	v_pk_mul_f32 v[58:59], v[58:59], v[102:103]
	v_pk_mul_f32 v[54:55], v[54:55], v[106:107]
	v_pk_mul_f32 v[50:51], v[50:51], v[110:111]
	v_pk_mul_f32 v[48:49], v[48:49], v[108:109]
; __device__ __forceinline__ void finishSM(f32x16& p0, f32x16& p1, float alpha, float& l_reg, bf16x8& pa0, bf16x8& pa1, bf16x8& pa2, bf16x8& pa3) {
;   for (int r = 0; r < 16; ++r) p1[r] = __builtin_amdgcn_exp2f(p1[r]);
;   float ps = 0; for (int r = 0; r < 16; ++r) ps += p0[r]; for (int r = 0; r < 16; ++r) ps += p1[r];
;   { auto rr = __builtin_amdgcn_permlane32_swap(__float_as_uint(ps), __float_as_uint(ps), false, false);
;     ps = __uint_as_float(rr[0]) + __uint_as_float(rr[1]); }
;   l_reg = l_reg * alpha + ps;
;     ...
;   PK4(p0, 0, pa0); PK4(p0, 8, pa1); PK4(p1, 0, pa2); PK4(p1, 8, pa3);
;     ...
; }
; __device__ __forceinline__ void qkt(f32x16& p0, f32x16& p1, const bf16* Ks, const bf16x8* qr, const f32x16& negm, int r32, int hi) {
; #pragma unroll
;   for (int d0 = 0; d0 < 8; ++d0) { int cb = (d0 * 16 + hi * 8) * 2;
;     bf16x8 b0 = *reinterpret_cast<const bf16x8*>((const char*)Ks + KSWZ(r32, cb));
;     bf16x8 b1 = *reinterpret_cast<const bf16x8*>((const char*)Ks + KSWZ(32 + r32, cb));
;     if (d0 == 0) { p0 = __builtin_amdgcn_mfma_f32_32x32x16_bf16(b0, qr[0], negm, 0, 0, 0); p1 = __builtin_amdgcn_mfma_f32_32x32x16_bf16(b1, qr[0], negm, 0, 0, 0); }
;     else { p0 = __builtin_amdgcn_mfma_f32_32x32x16_bf16(b0, qr[d0], p0, 0, 0, 0); p1 = __builtin_amdgcn_mfma_f32_32x32x16_bf16(b1, qr[d0], p1, 0, 0, 0); } }
; }
; __device__ __forceinline__ int v_st(int k, int c) { const int kk = (k & ~0xC) | ((k & 4) << 1) | ((k & 8) >> 1); return ((kk >> 3) * 4 + (c >> 5)) * 512 + ((kk & 7) * 32 + (c & 31)) * 2; }
; __device__ __forceinline__ int v_rd_base(int lane) { return ((lane & 3) << 3) | (((lane >> 2) & 3) << 6) | (((lane >> 4) & 1) << 5) | (((lane >> 5) & 1) << 8); }
; template <int OFF> __device__ __forceinline__ s16x4 tr_read(int vb) {
;   s16x4 r; asm volatile("ds_read_b64_tr_b16 %0, %1 offset:%2" : "=&v"(r) : "v"(vb), "i"(OFF) : "memory"); return r;
; }
; template <int D0> __device__ __forceinline__ void pv_one(f32x16& od, int vb, bf16x8 pa0, bf16x8 pa1, bf16x8 pa2, bf16x8 pa3) {
;   const s16x4 l0 = tr_read<v_rd_off(D0, 0, 0)>(vb), h0 = tr_read<v_rd_off(D0, 0, 1)>(vb), l1 = tr_read<v_rd_off(D0, 1, 0)>(vb), h1 = tr_read<v_rd_off(D0, 1, 1)>(vb);
;   const s16x4 l2 = tr_read<v_rd_off(D0, 2, 0)>(vb), h2 = tr_read<v_rd_off(D0, 2, 1)>(vb), l3 = tr_read<v_rd_off(D0, 3, 0)>(vb), h3 = tr_read<v_rd_off(D0, 3, 1)>(vb);
.LBB0_102:
	v_exp_f32_e32 v178, v128
	v_exp_f32_e32 v179, v130
	v_exp_f32_e32 v246, v129
	v_exp_f32_e32 v245, v131
	v_exp_f32_e32 v180, v132
	v_exp_f32_e32 v244, v133
	v_exp_f32_e32 v181, v134
	v_exp_f32_e32 v243, v135
	v_exp_f32_e32 v240, v136
	v_exp_f32_e32 v242, v137
	v_exp_f32_e32 v239, v138
	v_exp_f32_e32 v241, v139
	v_exp_f32_e32 v236, v140
	v_exp_f32_e32 v238, v141
	v_exp_f32_e32 v235, v142
	v_exp_f32_e32 v237, v143
	s_waitcnt vmcnt(2)
	s_waitcnt lgkmcnt(0)
	s_barrier
	ds_read_b128 v[186:189], v216 offset:40960
	ds_read_b128 v[96:99], v216 offset:32768
	v_add_f32_e32 v182, 0, v178
	v_add_f32_e32 v182, v246, v182
	v_add_f32_e32 v182, v179, v182
	v_add_f32_e32 v182, v245, v182
	s_waitcnt lgkmcnt(0)
	v_mfma_f32_32x32x16_bf16 v[128:143], v[96:99], v[146:149], v[80:95]
	v_add_f32_e32 v182, v180, v182
	v_add_f32_e32 v182, v244, v182
	v_add_f32_e32 v182, v181, v182
	v_add_f32_e32 v182, v243, v182
	v_add_f32_e32 v182, v240, v182
	v_add_f32_e32 v182, v242, v182
	v_add_f32_e32 v182, v239, v182
	v_mfma_f32_32x32x16_bf16 v[96:111], v[186:189], v[146:149], v[80:95]
	ds_read_b128 v[186:189], v224 offset:40960
	ds_read_b128 v[204:207], v224 offset:32768
	v_add_f32_e32 v182, v241, v182
	v_exp_f32_e32 v112, v112
	v_add_f32_e32 v182, v236, v182
	v_exp_f32_e32 v113, v113
	v_add_f32_e32 v182, v238, v182
	v_exp_f32_e32 v114, v114
	s_waitcnt lgkmcnt(0)
	v_mfma_f32_32x32x16_bf16 v[128:143], v[204:207], v[150:153], v[128:143]
	v_add_f32_e32 v182, v235, v182
	v_exp_f32_e32 v115, v115
	v_add_f32_e32 v182, v237, v182
	v_exp_f32_e32 v116, v116
	v_add_f32_e32 v182, v112, v182
	v_exp_f32_e32 v117, v117
	v_add_f32_e32 v182, v113, v182
	v_mfma_f32_32x32x16_bf16 v[96:111], v[186:189], v[150:153], v[96:111]
	ds_read_b128 v[186:189], v223 offset:40960
	ds_read_b128 v[204:207], v223 offset:32768
	v_exp_f32_e32 v118, v118
	v_add_f32_e32 v182, v114, v182
	v_exp_f32_e32 v119, v119
	v_add_f32_e32 v182, v115, v182
	v_exp_f32_e32 v120, v120
	v_add_f32_e32 v182, v116, v182
	s_waitcnt lgkmcnt(0)
	v_mfma_f32_32x32x16_bf16 v[128:143], v[204:207], v[154:157], v[128:143]
	v_exp_f32_e32 v121, v121
	v_add_f32_e32 v182, v117, v182
	v_exp_f32_e32 v122, v122
	v_add_f32_e32 v182, v118, v182
	v_exp_f32_e32 v123, v123
	v_add_f32_e32 v182, v119, v182
	v_exp_f32_e32 v124, v124
	v_mfma_f32_32x32x16_bf16 v[96:111], v[186:189], v[154:157], v[96:111]
	ds_read_b128 v[186:189], v221 offset:40960
	ds_read_b128 v[204:207], v221 offset:32768
	v_add_f32_e32 v182, v120, v182
	v_exp_f32_e32 v125, v125
	v_add_f32_e32 v182, v121, v182
	v_exp_f32_e32 v126, v126
	v_add_f32_e32 v182, v122, v182
	v_exp_f32_e32 v127, v127
	s_waitcnt lgkmcnt(0)
	v_mfma_f32_32x32x16_bf16 v[128:143], v[204:207], v[158:161], v[128:143]
	v_add_f32_e32 v182, v123, v182
	v_add_f32_e32 v182, v124, v182
	v_add_f32_e32 v182, v125, v182
	v_add_f32_e32 v182, v126, v182
	v_add_f32_e32 v233, v127, v182
	v_mov_b32_e32 v234, v233
	s_nop 1
	v_permlane32_swap_b32_e32 v233, v234
	v_mfma_f32_32x32x16_bf16 v[96:111], v[186:189], v[158:161], v[96:111]
	ds_read_b128 v[186:189], v222 offset:40960
	ds_read_b128 v[204:207], v222 offset:32768
	s_waitcnt lgkmcnt(0)
	v_mfma_f32_32x32x16_bf16 v[128:143], v[204:207], v[162:165], v[128:143]
	v_mfma_f32_32x32x16_bf16 v[96:111], v[186:189], v[162:165], v[96:111]
	ds_read_b128 v[186:189], v225 offset:40960
	ds_read_b128 v[204:207], v225 offset:32768
	s_waitcnt lgkmcnt(0)
	v_mfma_f32_32x32x16_bf16 v[128:143], v[204:207], v[166:169], v[128:143]
	v_mfma_f32_32x32x16_bf16 v[96:111], v[186:189], v[166:169], v[96:111]
	ds_read_b128 v[186:189], v226 offset:40960
	ds_read_b128 v[204:207], v226 offset:32768
	s_waitcnt lgkmcnt(0)
	v_mfma_f32_32x32x16_bf16 v[128:143], v[204:207], v[170:173], v[128:143]
	v_mfma_f32_32x32x16_bf16 v[96:111], v[186:189], v[170:173], v[96:111]
	ds_read_b128 v[186:189], v227 offset:40960
	ds_read_b128 v[204:207], v227 offset:32768
	v_cvt_pk_bf16_f32 v178, v178, v246
	v_cvt_pk_bf16_f32 v179, v179, v245
	v_cvt_pk_bf16_f32 v180, v180, v244
	v_cvt_pk_bf16_f32 v181, v181, v243
	s_nop 0
	v_permlane32_swap_b32_e32 v178, v180
	s_waitcnt lgkmcnt(0)
	v_mfma_f32_32x32x16_bf16 v[128:143], v[204:207], v[174:177], v[128:143]
	v_permlane32_swap_b32_e32 v179, v181
	v_mfma_f32_32x32x16_bf16 v[96:111], v[186:189], v[174:177], v[96:111]
	v_cvt_pk_bf16_f32 v186, v240, v242
	v_cvt_pk_bf16_f32 v187, v239, v241
	v_cvt_pk_bf16_f32 v188, v236, v238
	v_cvt_pk_bf16_f32 v189, v235, v237
	v_cvt_pk_bf16_f32 v204, v112, v113
	v_cvt_pk_bf16_f32 v205, v114, v115
	v_cvt_pk_bf16_f32 v206, v116, v117
	v_cvt_pk_bf16_f32 v207, v118, v119
	v_cvt_pk_bf16_f32 v236, v120, v121
	v_cvt_pk_bf16_f32 v237, v122, v123
	v_cvt_pk_bf16_f32 v238, v124, v125
	v_cvt_pk_bf16_f32 v239, v126, v127
	s_nop 0
	v_permlane32_swap_b32_e32 v186, v188
	v_permlane32_swap_b32_e32 v187, v189
	v_permlane32_swap_b32_e32 v204, v206
	v_permlane32_swap_b32_e32 v205, v207
	v_permlane32_swap_b32_e32 v236, v238
	v_permlane32_swap_b32_e32 v237, v239
	s_mov_b32 s58, s90
	s_mov_b32 s59, s91
	ds_read_b64_tr_b16 v[240:241], v212 offset:0
	ds_read_b64_tr_b16 v[242:243], v212 offset:0x800
	ds_read_b64_tr_b16 v[244:245], v212 offset:0x1000
	ds_read_b64_tr_b16 v[246:247], v212 offset:0x1800
	ds_read_b64_tr_b16 v[248:249], v212 offset:0x2000
	ds_read_b64_tr_b16 v[250:251], v212 offset:0x2800
	ds_read_b64_tr_b16 v[182:183], v212 offset:0x3000
	ds_read_b64_tr_b16 v[184:185], v212 offset:0x3800
	s_waitcnt lgkmcnt(0)
; #define SBAR() __builtin_amdgcn_sched_barrier(0)
; template <bool FIRST>
; __device__ __forceinline__ void partialSM(f32x16& p0, f32x16& p1, float& m_reg, f32x16& negm, float& alpha) {
;   float pmax = p0[0]; for (int r = 1; r < 16; ++r) pmax = fmaxf(pmax, p0[r]); for (int r = 0; r < 16; ++r) pmax = fmaxf(pmax, p1[r]);
;   { auto rr = __builtin_amdgcn_permlane32_swap(__float_as_uint(pmax), __float_as_uint(pmax), false, false);
;     pmax = fmaxf(__uint_as_float(rr[0]), __uint_as_float(rr[1])); }
;   if (!FIRST && __builtin_expect(__all(pmax <= THRL), 1)) { alpha = 1.f; }
; template <int D0> __device__ __forceinline__ void pv_one(f32x16& od, int vb, bf16x8 pa0, bf16x8 pa1, bf16x8 pa2, bf16x8 pa3) {
;   const s16x4 l0 = tr_read<v_rd_off(D0, 0, 0)>(vb), h0 = tr_read<v_rd_off(D0, 0, 1)>(vb), l1 = tr_read<v_rd_off(D0, 1, 0)>(vb), h1 = tr_read<v_rd_off(D0, 1, 1)>(vb);
;   const s16x4 l2 = tr_read<v_rd_off(D0, 2, 0)>(vb), h2 = tr_read<v_rd_off(D0, 2, 1)>(vb), l3 = tr_read<v_rd_off(D0, 3, 0)>(vb), h3 = tr_read<v_rd_off(D0, 3, 1)>(vb);
;   asm volatile("s_waitcnt lgkmcnt(0)" ::: "memory"); SBAR();
;     ...
;   od = __builtin_amdgcn_mfma_f32_32x32x16_bf16(pa0, PK(l0, h0), od, 0, 0, 0);
;   od = __builtin_amdgcn_mfma_f32_32x32x16_bf16(pa1, PK(l1, h1), od, 0, 0, 0);
;   od = __builtin_amdgcn_mfma_f32_32x32x16_bf16(pa2, PK(l2, h2), od, 0, 0, 0);
;   od = __builtin_amdgcn_mfma_f32_32x32x16_bf16(pa3, PK(l3, h3), od, 0, 0, 0);
;     ...
; }
; __device__ __forceinline__ void pv_d0(f32x16* o, int vb, bf16x8 pa0, bf16x8 pa1, bf16x8 pa2, bf16x8 pa3) {
;   pv_one<0>(o[0], vb, pa0, pa1, pa2, pa3); pv_one<1>(o[1], vb, pa0, pa1, pa2, pa3); pv_one<2>(o[2], vb, pa0, pa1, pa2, pa3); pv_one<3>(o[3], vb, pa0, pa1, pa2, pa3);
; }
	s_nop 0
	v_mfma_f32_32x32x16_bf16 v[0:15], v[178:181], v[240:243], v[0:15]
	v_mfma_f32_32x32x16_bf16 v[0:15], v[186:189], v[244:247], v[0:15]
	v_mfma_f32_32x32x16_bf16 v[0:15], v[204:207], v[248:251], v[0:15]
	v_mfma_f32_32x32x16_bf16 v[0:15], v[236:239], v[182:185], v[0:15]
	ds_read_b64_tr_b16 v[182:183], v212 offset:0x200
	ds_read_b64_tr_b16 v[184:185], v212 offset:0xa00
	ds_read_b64_tr_b16 v[240:241], v212 offset:0x1200
	ds_read_b64_tr_b16 v[242:243], v212 offset:0x1a00
	ds_read_b64_tr_b16 v[244:245], v212 offset:0x2200
	ds_read_b64_tr_b16 v[246:247], v212 offset:0x2a00
	ds_read_b64_tr_b16 v[248:249], v212 offset:0x3200
	ds_read_b64_tr_b16 v[250:251], v212 offset:0x3a00
	s_add_i32 m0, s98, 0xc000
	s_nop 0
	buffer_load_dwordx4 v64, s[56:59], s1 offen lds
	s_add_i32 m0, s98, 0xc400
	s_nop 0
	buffer_load_dwordx4 v65, s[56:59], s1 offen lds
	s_waitcnt lgkmcnt(0)
	s_nop 0
	v_mfma_f32_32x32x16_bf16 v[32:47], v[178:181], v[182:185], v[32:47]
	ds_read_b64_tr_b16 v[182:183], v212 offset:0x400
	ds_read_b64_tr_b16 v[184:185], v212 offset:0xc00
	v_mfma_f32_32x32x16_bf16 v[32:47], v[186:189], v[240:243], v[32:47]
	ds_read_b64_tr_b16 v[240:241], v212 offset:0x1400
	ds_read_b64_tr_b16 v[242:243], v212 offset:0x1c00
	v_mfma_f32_32x32x16_bf16 v[32:47], v[204:207], v[244:247], v[32:47]
	ds_read_b64_tr_b16 v[244:245], v212 offset:0x2400
	ds_read_b64_tr_b16 v[246:247], v212 offset:0x2c00
	v_mfma_f32_32x32x16_bf16 v[32:47], v[236:239], v[248:251], v[32:47]
	ds_read_b64_tr_b16 v[248:249], v212 offset:0x3400
	ds_read_b64_tr_b16 v[250:251], v212 offset:0x3c00
	s_waitcnt lgkmcnt(0)
	v_mfma_f32_32x32x16_bf16 v[16:31], v[178:181], v[182:185], v[16:31]
	ds_read_b64_tr_b16 v[182:183], v212 offset:0x600
	ds_read_b64_tr_b16 v[184:185], v212 offset:0xe00
	v_mfma_f32_32x32x16_bf16 v[16:31], v[186:189], v[240:243], v[16:31]
	ds_read_b64_tr_b16 v[240:241], v212 offset:0x1600
	ds_read_b64_tr_b16 v[242:243], v212 offset:0x1e00
	v_mfma_f32_32x32x16_bf16 v[16:31], v[204:207], v[244:247], v[16:31]
	ds_read_b64_tr_b16 v[244:245], v212 offset:0x2600
	ds_read_b64_tr_b16 v[246:247], v212 offset:0x2e00
	v_mfma_f32_32x32x16_bf16 v[16:31], v[236:239], v[248:251], v[16:31]
	ds_read_b64_tr_b16 v[248:249], v212 offset:0x3600
	ds_read_b64_tr_b16 v[250:251], v212 offset:0x3e00
	s_waitcnt lgkmcnt(0)
	s_barrier
	v_mfma_f32_32x32x16_bf16 v[48:63], v[178:181], v[182:185], v[48:63]
	s_add_i32 m0, s98, 0x4000
	s_nop 0
	buffer_load_dwordx4 v66, s[88:91], s1 offen lds
	v_max_f32_e32 v178, v129, v129
	v_max_f32_e32 v179, v128, v128
	v_max_f32_e32 v178, v179, v178
	v_max3_f32 v178, v178, v130, v131
	v_max3_f32 v178, v178, v132, v133
	v_max3_f32 v178, v178, v134, v135
	v_max3_f32 v178, v178, v136, v137
	v_mfma_f32_32x32x16_bf16 v[48:63], v[186:189], v[240:243], v[48:63]
	s_add_i32 m0, s98, 0x4400
	s_nop 0
	buffer_load_dwordx4 v67, s[88:91], s1 offen lds
	v_max3_f32 v178, v178, v138, v139
	v_max3_f32 v178, v178, v140, v141
	v_max3_f32 v178, v178, v142, v143
	v_max3_f32 v178, v178, v96, v97
	v_max3_f32 v178, v178, v98, v99
	v_max3_f32 v178, v178, v100, v101
	v_max3_f32 v178, v178, v102, v103
	v_mfma_f32_32x32x16_bf16 v[48:63], v[204:207], v[244:247], v[48:63]
	v_max3_f32 v178, v178, v104, v105
	v_max3_f32 v178, v178, v106, v107
	v_max3_f32 v178, v178, v108, v109
	v_max3_f32 v178, v178, v110, v111
	v_mov_b32_e32 v179, v178
	s_nop 1
	v_permlane32_swap_b32_e32 v178, v179
	v_mfma_f32_32x32x16_bf16 v[48:63], v[236:239], v[248:251], v[48:63]
	v_max_f32_e32 v179, v179, v179
	v_max_f32_e32 v178, v178, v178
	v_max_f32_e32 v179, v178, v179
	v_cmp_ge_f32_e32 vcc, s5, v179
	s_cmp_eq_u64 vcc, exec
	v_mov_b32_e32 v178, 1.0
	s_cbranch_scc0 .LBB0_110
.LBB0_103:
	v_cmp_gt_f32_e32 vcc, 1.0, v178
	s_cbranch_vccz .LBB0_107
	s_and_saveexec_b64 s[58:59], s[52:53]
	ds_write_b32 v211, v178 offset:128
	s_or_b64 exec, exec, s[58:59]
	s_waitcnt lgkmcnt(0)
	v_add_u32_e32 v124, v210, v194
	ds_read_b128 v[112:115], v124 offset:224
	ds_read_b128 v[116:119], v124 offset:192
	ds_read_b128 v[120:123], v124 offset:160
	ds_read_b128 v[124:127], v124 offset:128
	s_waitcnt lgkmcnt(3)
	v_pk_mul_f32 v[12:13], v[12:13], v[112:113]
	s_waitcnt lgkmcnt(2)
	v_pk_mul_f32 v[8:9], v[8:9], v[116:117]
	s_waitcnt lgkmcnt(1)
	v_pk_mul_f32 v[4:5], v[4:5], v[120:121]
	v_pk_mul_f32 v[14:15], v[14:15], v[114:115]
	v_pk_mul_f32 v[10:11], v[10:11], v[118:119]
	v_pk_mul_f32 v[6:7], v[6:7], v[122:123]
	s_waitcnt lgkmcnt(0)
	v_pk_mul_f32 v[2:3], v[2:3], v[126:127]
	v_pk_mul_f32 v[0:1], v[0:1], v[124:125]
	v_pk_mul_f32 v[44:45], v[44:45], v[112:113]
	v_pk_mul_f32 v[40:41], v[40:41], v[116:117]
	v_pk_mul_f32 v[36:37], v[36:37], v[120:121]
	v_pk_mul_f32 v[46:47], v[46:47], v[114:115]
	v_pk_mul_f32 v[42:43], v[42:43], v[118:119]
	v_pk_mul_f32 v[38:39], v[38:39], v[122:123]
	v_pk_mul_f32 v[34:35], v[34:35], v[126:127]
	v_pk_mul_f32 v[32:33], v[32:33], v[124:125]
	v_pk_mul_f32 v[28:29], v[28:29], v[112:113]
	v_pk_mul_f32 v[24:25], v[24:25], v[116:117]
	v_pk_mul_f32 v[20:21], v[20:21], v[120:121]
	v_pk_mul_f32 v[30:31], v[30:31], v[114:115]
	v_pk_mul_f32 v[26:27], v[26:27], v[118:119]
	v_pk_mul_f32 v[22:23], v[22:23], v[122:123]
	v_pk_mul_f32 v[18:19], v[18:19], v[126:127]
	v_pk_mul_f32 v[16:17], v[16:17], v[124:125]
	v_pk_mul_f32 v[60:61], v[60:61], v[112:113]
	v_pk_mul_f32 v[56:57], v[56:57], v[116:117]
	v_pk_mul_f32 v[52:53], v[52:53], v[120:121]
	v_pk_mul_f32 v[62:63], v[62:63], v[114:115]
	v_pk_mul_f32 v[58:59], v[58:59], v[118:119]
	v_pk_mul_f32 v[54:55], v[54:55], v[122:123]
	v_pk_mul_f32 v[50:51], v[50:51], v[126:127]
	v_pk_mul_f32 v[48:49], v[48:49], v[124:125]
